# residual GEMM epilogue (bf16 in-place stream): all 16 residual-row loads issued up front into dead operand registers instead of load-wait-store one row at a time
# speedup vs baseline: 1.0219x; 1.0219x over previous
.LBB0_374:
	s_add_u32 s16, s14, 0x100
	s_addc_u32 s17, s15, 0
	s_add_i32 s49, 0, 0x10000
	v_add_u32_e32 v154, s49, v164
	ds_read_b128 v[142:145], v154
	ds_read_b128 v[146:149], v154 offset:1024
	ds_read_b128 v[150:153], v154 offset:2048
	ds_read_b128 v[154:157], v154 offset:3072
	s_cmp_eq_u32 s48, 40
	s_cselect_b32 s21, s7, s17
	s_cselect_b32 s20, s6, s16
	s_cselect_b32 s19, s9, s47
	s_cselect_b32 s18, s8, s46
	v_lshl_add_u64 v[162:163], s[14:15], 0, v[138:139]
	s_add_i32 m0, s35, 0xc000
	ds_read_b128 v[158:161], v166
	ds_read_b128 v[168:171], v166 offset:1024
	ds_read_b128 v[172:175], v166 offset:2048
	ds_read_b128 v[190:193], v166 offset:3072
	ds_read_b128 v[194:197], v166 offset:4096
	ds_read_b128 v[198:201], v166 offset:5120
	ds_read_b128 v[202:205], v166 offset:6144
	ds_read_b128 v[206:209], v166 offset:7168
	global_load_lds_dwordx4 v[162:163], off
	v_lshl_add_u64 v[162:163], s[14:15], 0, v[140:141]
	s_add_i32 m0, s35, 0xe000
	s_nop 0
	global_load_lds_dwordx4 v[162:163], off
	s_waitcnt lgkmcnt(8)
	s_barrier
	s_waitcnt lgkmcnt(0)
	s_waitcnt lgkmcnt(0)
	v_mfma_f32_16x16x32_bf16 v[126:129], v[142:145], v[158:161], v[126:129]
	v_mfma_f32_16x16x32_bf16 v[122:125], v[150:153], v[158:161], v[122:125]
	v_mfma_f32_16x16x32_bf16 v[110:113], v[142:145], v[172:175], v[110:113]
	v_mfma_f32_16x16x32_bf16 v[106:109], v[150:153], v[172:175], v[106:109]
	v_mfma_f32_16x16x32_bf16 v[94:97], v[142:145], v[194:197], v[94:97]
	v_mfma_f32_16x16x32_bf16 v[90:93], v[150:153], v[194:197], v[90:93]
	v_mfma_f32_16x16x32_bf16 v[78:81], v[142:145], v[202:205], v[78:81]
	v_mfma_f32_16x16x32_bf16 v[74:77], v[150:153], v[202:205], v[74:77]
	v_mfma_f32_16x16x32_bf16 v[126:129], v[146:149], v[168:171], v[126:129]
	v_mfma_f32_16x16x32_bf16 v[122:125], v[154:157], v[168:171], v[122:125]
	v_mfma_f32_16x16x32_bf16 v[110:113], v[146:149], v[190:193], v[110:113]
	v_mfma_f32_16x16x32_bf16 v[106:109], v[154:157], v[190:193], v[106:109]
	v_mfma_f32_16x16x32_bf16 v[94:97], v[146:149], v[198:201], v[94:97]
	v_mfma_f32_16x16x32_bf16 v[90:93], v[154:157], v[198:201], v[90:93]
	v_mfma_f32_16x16x32_bf16 v[78:81], v[146:149], v[206:209], v[78:81]
	v_mfma_f32_16x16x32_bf16 v[74:77], v[154:157], v[206:209], v[74:77]
	s_barrier
	s_add_i32 s50, 0, 0x14000
	v_add_u32_e32 v162, s50, v164
	s_add_i32 s14, s49, s34
	ds_read_b128 v[210:213], v162
	ds_read_b128 v[214:217], v162 offset:1024
	ds_read_b128 v[218:221], v162 offset:2048
	ds_read_b128 v[222:225], v162 offset:3072
	s_add_u32 s64, s18, 0x80
	s_addc_u32 s65, s19, 0
	s_mov_b32 m0, s14
	s_nop 0
	global_load_lds_dwordx4 v132, s[18:19]
	s_add_i32 m0, s14, 0x2000
	s_nop 0
	global_load_lds_dwordx4 v136, s[18:19]
	s_barrier
	s_waitcnt lgkmcnt(0)
	s_waitcnt lgkmcnt(0)
	v_mfma_f32_16x16x32_bf16 v[118:121], v[210:213], v[158:161], v[118:121]
	v_mfma_f32_16x16x32_bf16 v[114:117], v[218:221], v[158:161], v[114:117]
	v_mfma_f32_16x16x32_bf16 v[102:105], v[210:213], v[172:175], v[102:105]
	v_mfma_f32_16x16x32_bf16 v[98:101], v[218:221], v[172:175], v[98:101]
	v_mfma_f32_16x16x32_bf16 v[86:89], v[210:213], v[194:197], v[86:89]
	v_mfma_f32_16x16x32_bf16 v[82:85], v[218:221], v[194:197], v[82:85]
	v_mfma_f32_16x16x32_bf16 v[70:73], v[210:213], v[202:205], v[70:73]
	v_mfma_f32_16x16x32_bf16 v[66:69], v[218:221], v[202:205], v[66:69]
	v_mfma_f32_16x16x32_bf16 v[118:121], v[214:217], v[168:171], v[118:121]
	v_mfma_f32_16x16x32_bf16 v[114:117], v[222:225], v[168:171], v[114:117]
	v_mfma_f32_16x16x32_bf16 v[102:105], v[214:217], v[190:193], v[102:105]
	v_mfma_f32_16x16x32_bf16 v[98:101], v[222:225], v[190:193], v[98:101]
	v_mfma_f32_16x16x32_bf16 v[86:89], v[214:217], v[198:201], v[86:89]
	v_mfma_f32_16x16x32_bf16 v[82:85], v[222:225], v[198:201], v[82:85]
	v_mfma_f32_16x16x32_bf16 v[70:73], v[214:217], v[206:209], v[70:73]
	v_mfma_f32_16x16x32_bf16 v[66:69], v[222:225], v[206:209], v[66:69]
	s_barrier
	s_mov_b32 m0, s35
	s_add_u32 s62, s20, 0x80
	s_addc_u32 s63, s21, 0
	ds_read_b128 v[158:161], v166 offset:16384
	ds_read_b128 v[168:171], v166 offset:17408
	ds_read_b128 v[172:175], v166 offset:18432
	ds_read_b128 v[190:193], v166 offset:19456
	ds_read_b128 v[194:197], v166 offset:20480
	ds_read_b128 v[198:201], v166 offset:21504
	ds_read_b128 v[202:205], v166 offset:22528
	ds_read_b128 v[206:209], v166 offset:23552
	global_load_lds_dwordx4 v130, s[20:21]
	s_mov_b32 m0, s36
	s_nop 0
	global_load_lds_dwordx4 v134, s[20:21]
	s_barrier
	s_waitcnt lgkmcnt(0)
	s_waitcnt lgkmcnt(0)
	v_mfma_f32_16x16x32_bf16 v[62:65], v[142:145], v[158:161], v[62:65]
	v_mfma_f32_16x16x32_bf16 v[58:61], v[150:153], v[158:161], v[58:61]
	v_mfma_f32_16x16x32_bf16 v[46:49], v[142:145], v[172:175], v[46:49]
	v_mfma_f32_16x16x32_bf16 v[42:45], v[150:153], v[172:175], v[42:45]
	v_mfma_f32_16x16x32_bf16 v[30:33], v[142:145], v[194:197], v[30:33]
	v_mfma_f32_16x16x32_bf16 v[26:29], v[150:153], v[194:197], v[26:29]
	v_mfma_f32_16x16x32_bf16 v[14:17], v[142:145], v[202:205], v[14:17]
	v_mfma_f32_16x16x32_bf16 v[10:13], v[150:153], v[202:205], v[10:13]
	v_mfma_f32_16x16x32_bf16 v[62:65], v[146:149], v[168:171], v[62:65]
	v_mfma_f32_16x16x32_bf16 v[58:61], v[154:157], v[168:171], v[58:61]
	v_mfma_f32_16x16x32_bf16 v[46:49], v[146:149], v[190:193], v[46:49]
	v_mfma_f32_16x16x32_bf16 v[42:45], v[154:157], v[190:193], v[42:45]
	v_mfma_f32_16x16x32_bf16 v[30:33], v[146:149], v[198:201], v[30:33]
	v_mfma_f32_16x16x32_bf16 v[26:29], v[154:157], v[198:201], v[26:29]
	v_mfma_f32_16x16x32_bf16 v[14:17], v[146:149], v[206:209], v[14:17]
	v_mfma_f32_16x16x32_bf16 v[10:13], v[154:157], v[206:209], v[10:13]
	s_barrier
	s_add_u32 s14, s18, 0xb0000
	s_addc_u32 s15, s19, 0
	s_add_i32 s49, s50, s34
	s_mov_b32 m0, s49
	s_nop 0
	global_load_lds_dwordx4 v132, s[14:15]
	s_add_i32 m0, s49, 0x2000
	s_nop 0
	global_load_lds_dwordx4 v136, s[14:15]
	s_waitcnt vmcnt(6)
	s_barrier
	v_mfma_f32_16x16x32_bf16 v[54:57], v[210:213], v[158:161], v[54:57]
	v_mfma_f32_16x16x32_bf16 v[50:53], v[218:221], v[158:161], v[50:53]
	v_mfma_f32_16x16x32_bf16 v[38:41], v[210:213], v[172:175], v[38:41]
	v_mfma_f32_16x16x32_bf16 v[34:37], v[218:221], v[172:175], v[34:37]
	v_mfma_f32_16x16x32_bf16 v[22:25], v[210:213], v[194:197], v[22:25]
	v_mfma_f32_16x16x32_bf16 v[18:21], v[218:221], v[194:197], v[18:21]
	v_mfma_f32_16x16x32_bf16 v[6:9], v[210:213], v[202:205], v[6:9]
	v_mfma_f32_16x16x32_bf16 v[2:5], v[218:221], v[202:205], v[2:5]
	v_mfma_f32_16x16x32_bf16 v[54:57], v[214:217], v[168:171], v[54:57]
	v_mfma_f32_16x16x32_bf16 v[50:53], v[222:225], v[168:171], v[50:53]
	v_mfma_f32_16x16x32_bf16 v[38:41], v[214:217], v[190:193], v[38:41]
	v_mfma_f32_16x16x32_bf16 v[34:37], v[222:225], v[190:193], v[34:37]
	v_mfma_f32_16x16x32_bf16 v[22:25], v[214:217], v[198:201], v[22:25]
	v_mfma_f32_16x16x32_bf16 v[18:21], v[222:225], v[198:201], v[18:21]
	v_mfma_f32_16x16x32_bf16 v[6:9], v[214:217], v[206:209], v[6:9]
	v_mfma_f32_16x16x32_bf16 v[2:5], v[222:225], v[206:209], v[2:5]
	s_barrier
	s_add_i32 s49, 0, 0x18000
	v_add_u32_e32 v154, s49, v164
	ds_read_b128 v[142:145], v154
	ds_read_b128 v[146:149], v154 offset:1024
	ds_read_b128 v[150:153], v154 offset:2048
	ds_read_b128 v[154:157], v154 offset:3072
	s_add_u32 s14, s20, 0xb8000
	s_addc_u32 s15, s21, 0
	s_mov_b32 m0, s37
	ds_read_b128 v[158:161], v166 offset:32768
	ds_read_b128 v[168:171], v166 offset:33792
	ds_read_b128 v[172:175], v166 offset:34816
	ds_read_b128 v[190:193], v166 offset:35840
	ds_read_b128 v[194:197], v166 offset:36864
	ds_read_b128 v[198:201], v166 offset:37888
	ds_read_b128 v[202:205], v166 offset:38912
	ds_read_b128 v[206:209], v166 offset:39936
	global_load_lds_dwordx4 v130, s[14:15]
	s_mov_b32 m0, s38
	s_nop 0
	global_load_lds_dwordx4 v134, s[14:15]
	s_waitcnt lgkmcnt(8)
	s_barrier
	s_waitcnt lgkmcnt(0)
	s_waitcnt lgkmcnt(0)
	v_mfma_f32_16x16x32_bf16 v[126:129], v[142:145], v[158:161], v[126:129]
	v_mfma_f32_16x16x32_bf16 v[122:125], v[150:153], v[158:161], v[122:125]
	v_mfma_f32_16x16x32_bf16 v[110:113], v[142:145], v[172:175], v[110:113]
	v_mfma_f32_16x16x32_bf16 v[106:109], v[150:153], v[172:175], v[106:109]
	v_mfma_f32_16x16x32_bf16 v[94:97], v[142:145], v[194:197], v[94:97]
	v_mfma_f32_16x16x32_bf16 v[90:93], v[150:153], v[194:197], v[90:93]
	v_mfma_f32_16x16x32_bf16 v[78:81], v[142:145], v[202:205], v[78:81]
	v_mfma_f32_16x16x32_bf16 v[74:77], v[150:153], v[202:205], v[74:77]
	v_mfma_f32_16x16x32_bf16 v[126:129], v[146:149], v[168:171], v[126:129]
	v_mfma_f32_16x16x32_bf16 v[122:125], v[154:157], v[168:171], v[122:125]
	v_mfma_f32_16x16x32_bf16 v[110:113], v[146:149], v[190:193], v[110:113]
	v_mfma_f32_16x16x32_bf16 v[106:109], v[154:157], v[190:193], v[106:109]
	v_mfma_f32_16x16x32_bf16 v[94:97], v[146:149], v[198:201], v[94:97]
	v_mfma_f32_16x16x32_bf16 v[90:93], v[154:157], v[198:201], v[90:93]
	v_mfma_f32_16x16x32_bf16 v[78:81], v[146:149], v[206:209], v[78:81]
	v_mfma_f32_16x16x32_bf16 v[74:77], v[154:157], v[206:209], v[74:77]
	s_barrier
	s_add_i32 s20, 0, 0x1c000
	s_add_i32 s14, s49, s34
	v_add_u32_e32 v167, s20, v164
	s_mov_b32 m0, s14
	ds_read_b128 v[210:213], v167
	ds_read_b128 v[214:217], v167 offset:1024
	ds_read_b128 v[218:221], v167 offset:2048
	ds_read_b128 v[222:225], v167 offset:3072
	global_load_lds_dwordx4 v132, s[64:65]
	s_add_i32 m0, s14, 0x2000
	s_nop 0
	global_load_lds_dwordx4 v136, s[64:65]
	s_barrier
	s_waitcnt lgkmcnt(0)
	s_waitcnt lgkmcnt(0)
	v_mfma_f32_16x16x32_bf16 v[118:121], v[210:213], v[158:161], v[118:121]
	v_mfma_f32_16x16x32_bf16 v[114:117], v[218:221], v[158:161], v[114:117]
	v_mfma_f32_16x16x32_bf16 v[102:105], v[210:213], v[172:175], v[102:105]
	v_mfma_f32_16x16x32_bf16 v[98:101], v[218:221], v[172:175], v[98:101]
	v_mfma_f32_16x16x32_bf16 v[86:89], v[210:213], v[194:197], v[86:89]
	v_mfma_f32_16x16x32_bf16 v[82:85], v[218:221], v[194:197], v[82:85]
	v_mfma_f32_16x16x32_bf16 v[70:73], v[210:213], v[202:205], v[70:73]
	v_mfma_f32_16x16x32_bf16 v[66:69], v[218:221], v[202:205], v[66:69]
	v_mfma_f32_16x16x32_bf16 v[118:121], v[214:217], v[168:171], v[118:121]
	v_mfma_f32_16x16x32_bf16 v[114:117], v[222:225], v[168:171], v[114:117]
	v_mfma_f32_16x16x32_bf16 v[102:105], v[214:217], v[190:193], v[102:105]
	v_mfma_f32_16x16x32_bf16 v[98:101], v[222:225], v[190:193], v[98:101]
	v_mfma_f32_16x16x32_bf16 v[86:89], v[214:217], v[198:201], v[86:89]
	v_mfma_f32_16x16x32_bf16 v[82:85], v[222:225], v[198:201], v[82:85]
	v_mfma_f32_16x16x32_bf16 v[70:73], v[214:217], v[206:209], v[70:73]
	v_mfma_f32_16x16x32_bf16 v[66:69], v[222:225], v[206:209], v[66:69]
	s_barrier
	s_mov_b32 m0, s39
	ds_read_b128 v[158:161], v166 offset:49152
	ds_read_b128 v[168:171], v166 offset:50176
	ds_read_b128 v[172:175], v166 offset:51200
	ds_read_b128 v[190:193], v166 offset:52224
	ds_read_b128 v[194:197], v166 offset:53248
	ds_read_b128 v[198:201], v166 offset:54272
	ds_read_b128 v[202:205], v166 offset:55296
	ds_read_b128 v[206:209], v166 offset:56320
	global_load_lds_dwordx4 v130, s[62:63]
	s_mov_b32 m0, s40
	s_nop 0
	global_load_lds_dwordx4 v134, s[62:63]
	s_barrier
	s_waitcnt lgkmcnt(0)
	s_waitcnt lgkmcnt(0)
	v_mfma_f32_16x16x32_bf16 v[62:65], v[142:145], v[158:161], v[62:65]
	v_mfma_f32_16x16x32_bf16 v[58:61], v[150:153], v[158:161], v[58:61]
	v_mfma_f32_16x16x32_bf16 v[46:49], v[142:145], v[172:175], v[46:49]
	v_mfma_f32_16x16x32_bf16 v[42:45], v[150:153], v[172:175], v[42:45]
	v_mfma_f32_16x16x32_bf16 v[30:33], v[142:145], v[194:197], v[30:33]
	v_mfma_f32_16x16x32_bf16 v[26:29], v[150:153], v[194:197], v[26:29]
	v_mfma_f32_16x16x32_bf16 v[14:17], v[142:145], v[202:205], v[14:17]
	v_mfma_f32_16x16x32_bf16 v[10:13], v[150:153], v[202:205], v[10:13]
	v_mfma_f32_16x16x32_bf16 v[62:65], v[146:149], v[168:171], v[62:65]
	v_mfma_f32_16x16x32_bf16 v[58:61], v[154:157], v[168:171], v[58:61]
	v_mfma_f32_16x16x32_bf16 v[46:49], v[146:149], v[190:193], v[46:49]
	v_mfma_f32_16x16x32_bf16 v[42:45], v[154:157], v[190:193], v[42:45]
	v_mfma_f32_16x16x32_bf16 v[30:33], v[146:149], v[198:201], v[30:33]
	v_mfma_f32_16x16x32_bf16 v[26:29], v[154:157], v[198:201], v[26:29]
	v_mfma_f32_16x16x32_bf16 v[14:17], v[146:149], v[206:209], v[14:17]
	v_mfma_f32_16x16x32_bf16 v[10:13], v[154:157], v[206:209], v[10:13]
	s_barrier
	s_add_u32 s14, s18, 0xb0080
	s_addc_u32 s15, s19, 0
	s_add_i32 s18, s20, s34
	s_mov_b32 m0, s18
	s_nop 0
	global_load_lds_dwordx4 v132, s[14:15]
	s_add_i32 m0, s18, 0x2000
	s_nop 0
	global_load_lds_dwordx4 v136, s[14:15]
	s_waitcnt vmcnt(6)
	s_barrier
	v_mfma_f32_16x16x32_bf16 v[54:57], v[210:213], v[158:161], v[54:57]
	v_mfma_f32_16x16x32_bf16 v[50:53], v[218:221], v[158:161], v[50:53]
	v_mfma_f32_16x16x32_bf16 v[38:41], v[210:213], v[172:175], v[38:41]
	v_mfma_f32_16x16x32_bf16 v[34:37], v[218:221], v[172:175], v[34:37]
	v_mfma_f32_16x16x32_bf16 v[22:25], v[210:213], v[194:197], v[22:25]
	v_mfma_f32_16x16x32_bf16 v[18:21], v[218:221], v[194:197], v[18:21]
	v_mfma_f32_16x16x32_bf16 v[6:9], v[210:213], v[202:205], v[6:9]
	v_mfma_f32_16x16x32_bf16 v[2:5], v[218:221], v[202:205], v[2:5]
	v_mfma_f32_16x16x32_bf16 v[54:57], v[214:217], v[168:171], v[54:57]
	v_mfma_f32_16x16x32_bf16 v[50:53], v[222:225], v[168:171], v[50:53]
	v_mfma_f32_16x16x32_bf16 v[38:41], v[214:217], v[190:193], v[38:41]
	v_mfma_f32_16x16x32_bf16 v[34:37], v[222:225], v[190:193], v[34:37]
	v_mfma_f32_16x16x32_bf16 v[22:25], v[214:217], v[198:201], v[22:25]
	v_mfma_f32_16x16x32_bf16 v[18:21], v[222:225], v[198:201], v[18:21]
	v_mfma_f32_16x16x32_bf16 v[6:9], v[214:217], v[206:209], v[6:9]
	v_mfma_f32_16x16x32_bf16 v[2:5], v[222:225], v[206:209], v[2:5]
	s_barrier
	s_add_i32 s48, s48, 2
	s_add_u32 s46, s46, 0x100
	s_addc_u32 s47, s47, 0
	s_cmp_gt_u32 s48, 41
	s_mov_b64 s[14:15], s[16:17]
	s_cbranch_scc0 .LBB0_374
	s_ashr_i32 s14, s33, 5
	s_mul_hi_i32 s15, s14, 0x9000
	s_mul_i32 s14, s14, 0x9000
	v_lshl_or_b32 v158, s45, 8, v165
	s_add_u32 s14, s26, s14
	s_addc_u32 s15, s27, s15
	v_ashrrev_i32_e32 v159, 31, v158
	v_lshl_add_u64 v[160:161], v[158:159], 2, s[14:15]
	global_load_dwordx4 v[142:145], v[160:161], off offset:16
	global_load_dwordx4 v[146:149], v[160:161], off
	v_lshl_add_u32 v162, s33, 8, v1
	v_ashrrev_i32_e32 v163, 31, v162
	v_lshlrev_b64 v[150:151], 12, v[162:163]
	v_lshl_add_u64 v[150:151], s[12:13], 0, v[150:151]
	v_lshl_add_u64 v[150:151], v[158:159], 1, v[150:151]
	v_mov_b32_e32 v152, 0x10000
	v_mov_b32_e32 v153, 0
	global_load_dwordx4 v[174:177], v[150:151], off offset:2048
	global_load_dwordx4 v[186:189], v[150:151], off offset:2304
	v_lshl_add_u64 v[150:151], v[150:151], 0, v[152:153]
	global_load_dwordx4 v[190:193], v[150:151], off offset:2048
	global_load_dwordx4 v[194:197], v[150:151], off offset:2304
	v_lshl_add_u64 v[150:151], v[150:151], 0, v[152:153]
	global_load_dwordx4 v[198:201], v[150:151], off offset:2048
	global_load_dwordx4 v[202:205], v[150:151], off offset:2304
	v_lshl_add_u64 v[150:151], v[150:151], 0, v[152:153]
	global_load_dwordx4 v[206:209], v[150:151], off offset:2048
	global_load_dwordx4 v[210:213], v[150:151], off offset:2304
	v_mov_b32_e32 v152, 0x50000
	v_lshl_add_u64 v[150:151], v[150:151], 0, v[152:153]
	v_mov_b32_e32 v152, 0x10000
	global_load_dwordx4 v[214:217], v[150:151], off offset:2048
	global_load_dwordx4 v[218:221], v[150:151], off offset:2304
	v_lshl_add_u64 v[150:151], v[150:151], 0, v[152:153]
	global_load_dwordx4 v[222:225], v[150:151], off offset:2048
	global_load_dwordx4 v[226:229], v[150:151], off offset:2304
	v_lshl_add_u64 v[150:151], v[150:151], 0, v[152:153]
	global_load_dwordx4 v[230:233], v[150:151], off offset:2048
	global_load_dwordx4 v[236:239], v[150:151], off offset:2304
	v_lshl_add_u64 v[150:151], v[150:151], 0, v[152:153]
	global_load_dwordx4 v[246:249], v[150:151], off offset:2048
	global_load_dwordx4 v[250:253], v[150:151], off offset:2304
	s_mov_b64 s[14:15], 0x80000
	s_and_b64 vcc, exec, s[4:5]
	s_mov_b32 s45, s43
	s_mov_b32 s33, s44
	s_mov_b64 s[16:17], s[8:9]
	s_waitcnt vmcnt(0)
	v_pk_add_f32 v[144:145], v[144:145], 1.0 op_sel_hi:[1,0]
	v_pk_add_f32 v[148:149], v[148:149], 1.0 op_sel_hi:[1,0]
	v_pk_add_f32 v[146:147], v[146:147], 1.0 op_sel_hi:[1,0]
	v_pk_add_f32 v[142:143], v[142:143], 1.0 op_sel_hi:[1,0]
	v_pk_mul_f32 v[152:153], v[148:149], 0.5 op_sel_hi:[1,0]
	v_pk_mul_f32 v[156:157], v[146:147], 0.5 op_sel_hi:[1,0]
	v_pk_mul_f32 v[150:151], v[144:145], 0.5 op_sel_hi:[1,0]
	v_pk_mul_f32 v[154:155], v[142:143], 0.5 op_sel_hi:[1,0]
	global_load_dwordx4 v[142:145], v[160:161], off offset:528
	global_load_dwordx4 v[146:149], v[160:161], off offset:512
	s_waitcnt vmcnt(0)
	v_pk_add_f32 v[144:145], v[144:145], 1.0 op_sel_hi:[1,0]
	v_pk_add_f32 v[148:149], v[148:149], 1.0 op_sel_hi:[1,0]
	v_pk_add_f32 v[160:161], v[146:147], 1.0 op_sel_hi:[1,0]
	v_pk_mul_f32 v[146:147], v[148:149], 0.5 op_sel_hi:[1,0]
	v_pk_mul_f32 v[148:149], v[160:161], 0.5 op_sel_hi:[1,0]
	v_pk_add_f32 v[160:161], v[142:143], 1.0 op_sel_hi:[1,0]
	v_pk_mul_f32 v[142:143], v[144:145], 0.5 op_sel_hi:[1,0]
	v_pk_mul_f32 v[144:145], v[160:161], 0.5 op_sel_hi:[1,0]
	v_lshlrev_b64 v[160:161], 12, v[162:163]
	v_lshl_add_u64 v[168:169], s[12:13], 0, v[160:161]
	v_lshlrev_b64 v[160:161], 1, v[158:159]
	v_lshl_add_u64 v[158:159], v[168:169], 0, v[160:161]
	v_mov_b32_e32 v168, v174
	v_mov_b32_e32 v169, v175
	v_mov_b32_e32 v170, v176
	v_mov_b32_e32 v171, v177
	s_nop 0
	v_lshlrev_b32_e32 v172, 16, v168
	v_and_b32_e32 v173, 0xffff0000, v168
	v_lshlrev_b32_e32 v168, 16, v169
	v_and_b32_e32 v169, 0xffff0000, v169
	v_pk_fma_f32 v[128:129], v[128:129], v[152:153], v[168:169]
	v_lshlrev_b32_e32 v168, 16, v170
	v_and_b32_e32 v169, 0xffff0000, v170
	v_pk_fma_f32 v[168:169], v[122:123], v[154:155], v[168:169]
	v_lshlrev_b32_e32 v122, 16, v171
	v_and_b32_e32 v123, 0xffff0000, v171
	v_pk_fma_f32 v[126:127], v[126:127], v[156:157], v[172:173]
	v_pk_fma_f32 v[170:171], v[124:125], v[150:151], v[122:123]
	v_cvt_pk_bf16_f32 v122, v126, v127
	v_cvt_pk_bf16_f32 v123, v128, v129
	v_cvt_pk_bf16_f32 v124, v168, v169
	v_cvt_pk_bf16_f32 v125, v170, v171
	global_store_dwordx4 v[158:159], v[122:125], off offset:2048
	s_nop 1
	v_mov_b32_e32 v122, v186
	v_mov_b32_e32 v123, v187
	v_mov_b32_e32 v124, v188
	v_mov_b32_e32 v125, v189
	s_nop 0
	v_lshlrev_b32_e32 v126, 16, v122
	v_and_b32_e32 v127, 0xffff0000, v122
	v_lshlrev_b32_e32 v122, 16, v123
	v_and_b32_e32 v123, 0xffff0000, v123
	v_pk_fma_f32 v[120:121], v[120:121], v[146:147], v[122:123]
	v_lshlrev_b32_e32 v122, 16, v124
	v_and_b32_e32 v123, 0xffff0000, v124
	v_pk_fma_f32 v[122:123], v[114:115], v[144:145], v[122:123]
	v_lshlrev_b32_e32 v114, 16, v125
	v_and_b32_e32 v115, 0xffff0000, v125
	v_pk_fma_f32 v[118:119], v[118:119], v[148:149], v[126:127]
	v_pk_fma_f32 v[124:125], v[116:117], v[142:143], v[114:115]
	v_cvt_pk_bf16_f32 v114, v118, v119
	v_cvt_pk_bf16_f32 v115, v120, v121
	v_cvt_pk_bf16_f32 v116, v122, v123
	v_cvt_pk_bf16_f32 v117, v124, v125
	global_store_dwordx4 v[158:159], v[114:117], off offset:2304
	s_nop 1
	v_or_b32_e32 v114, 16, v162
	v_ashrrev_i32_e32 v115, 31, v114
	v_lshlrev_b64 v[114:115], 12, v[114:115]
	v_lshl_add_u64 v[114:115], s[12:13], 0, v[114:115]
	v_lshl_add_u64 v[118:119], v[114:115], 0, v[160:161]
	v_mov_b32_e32 v114, v190
	v_mov_b32_e32 v115, v191
	v_mov_b32_e32 v116, v192
	v_mov_b32_e32 v117, v193
	s_nop 0
	v_lshlrev_b32_e32 v120, 16, v114
	v_and_b32_e32 v121, 0xffff0000, v114
	v_lshlrev_b32_e32 v114, 16, v115
	v_and_b32_e32 v115, 0xffff0000, v115
	v_pk_fma_f32 v[112:113], v[112:113], v[152:153], v[114:115]
	v_lshlrev_b32_e32 v114, 16, v116
	v_and_b32_e32 v115, 0xffff0000, v116
	v_pk_fma_f32 v[114:115], v[106:107], v[154:155], v[114:115]
	v_lshlrev_b32_e32 v106, 16, v117
	v_and_b32_e32 v107, 0xffff0000, v117
	v_pk_fma_f32 v[110:111], v[110:111], v[156:157], v[120:121]
	v_pk_fma_f32 v[116:117], v[108:109], v[150:151], v[106:107]
	v_cvt_pk_bf16_f32 v106, v110, v111
	v_cvt_pk_bf16_f32 v107, v112, v113
	v_cvt_pk_bf16_f32 v108, v114, v115
	v_cvt_pk_bf16_f32 v109, v116, v117
	global_store_dwordx4 v[118:119], v[106:109], off offset:2048
	s_nop 1
	v_mov_b32_e32 v106, v194
	v_mov_b32_e32 v107, v195
	v_mov_b32_e32 v108, v196
	v_mov_b32_e32 v109, v197
	s_nop 0
	v_lshlrev_b32_e32 v110, 16, v106
	v_and_b32_e32 v111, 0xffff0000, v106
	v_lshlrev_b32_e32 v106, 16, v107
	v_and_b32_e32 v107, 0xffff0000, v107
	v_pk_fma_f32 v[104:105], v[104:105], v[146:147], v[106:107]
	v_lshlrev_b32_e32 v106, 16, v108
	v_and_b32_e32 v107, 0xffff0000, v108
	v_pk_fma_f32 v[106:107], v[98:99], v[144:145], v[106:107]
	v_lshlrev_b32_e32 v98, 16, v109
	v_and_b32_e32 v99, 0xffff0000, v109
	v_pk_fma_f32 v[102:103], v[102:103], v[148:149], v[110:111]
	v_pk_fma_f32 v[108:109], v[100:101], v[142:143], v[98:99]
	v_cvt_pk_bf16_f32 v98, v102, v103
	v_cvt_pk_bf16_f32 v99, v104, v105
	v_cvt_pk_bf16_f32 v100, v106, v107
	v_cvt_pk_bf16_f32 v101, v108, v109
	global_store_dwordx4 v[118:119], v[98:101], off offset:2304
	s_nop 1
	v_or_b32_e32 v98, 32, v162
	v_ashrrev_i32_e32 v99, 31, v98
	v_lshlrev_b64 v[98:99], 12, v[98:99]
	v_lshl_add_u64 v[98:99], s[12:13], 0, v[98:99]
	v_lshl_add_u64 v[102:103], v[98:99], 0, v[160:161]
	v_mov_b32_e32 v98, v198
	v_mov_b32_e32 v99, v199
	v_mov_b32_e32 v100, v200
	v_mov_b32_e32 v101, v201
	s_nop 0
	v_lshlrev_b32_e32 v104, 16, v98
	v_and_b32_e32 v105, 0xffff0000, v98
	v_lshlrev_b32_e32 v98, 16, v99
	v_and_b32_e32 v99, 0xffff0000, v99
	v_pk_fma_f32 v[96:97], v[96:97], v[152:153], v[98:99]
	v_lshlrev_b32_e32 v98, 16, v100
	v_and_b32_e32 v99, 0xffff0000, v100
	v_pk_fma_f32 v[98:99], v[90:91], v[154:155], v[98:99]
	v_lshlrev_b32_e32 v90, 16, v101
	v_and_b32_e32 v91, 0xffff0000, v101
	v_pk_fma_f32 v[94:95], v[94:95], v[156:157], v[104:105]
	v_pk_fma_f32 v[100:101], v[92:93], v[150:151], v[90:91]
	v_cvt_pk_bf16_f32 v90, v94, v95
	v_cvt_pk_bf16_f32 v91, v96, v97
	v_cvt_pk_bf16_f32 v92, v98, v99
	v_cvt_pk_bf16_f32 v93, v100, v101
	global_store_dwordx4 v[102:103], v[90:93], off offset:2048
	s_nop 1
	v_mov_b32_e32 v90, v202
	v_mov_b32_e32 v91, v203
	v_mov_b32_e32 v92, v204
	v_mov_b32_e32 v93, v205
	s_nop 0
	v_lshlrev_b32_e32 v94, 16, v90
	v_and_b32_e32 v95, 0xffff0000, v90
	v_lshlrev_b32_e32 v90, 16, v91
	v_and_b32_e32 v91, 0xffff0000, v91
	v_pk_fma_f32 v[88:89], v[88:89], v[146:147], v[90:91]
	v_lshlrev_b32_e32 v90, 16, v92
	v_and_b32_e32 v91, 0xffff0000, v92
	v_pk_fma_f32 v[90:91], v[82:83], v[144:145], v[90:91]
	v_lshlrev_b32_e32 v82, 16, v93
	v_and_b32_e32 v83, 0xffff0000, v93
	v_pk_fma_f32 v[86:87], v[86:87], v[148:149], v[94:95]
	v_pk_fma_f32 v[92:93], v[84:85], v[142:143], v[82:83]
	v_cvt_pk_bf16_f32 v82, v86, v87
	v_cvt_pk_bf16_f32 v83, v88, v89
	v_cvt_pk_bf16_f32 v84, v90, v91
	v_cvt_pk_bf16_f32 v85, v92, v93
	global_store_dwordx4 v[102:103], v[82:85], off offset:2304
	s_nop 1
	v_or_b32_e32 v82, 48, v162
	v_ashrrev_i32_e32 v83, 31, v82
	v_lshlrev_b64 v[82:83], 12, v[82:83]
	v_lshl_add_u64 v[82:83], s[12:13], 0, v[82:83]
	v_lshl_add_u64 v[82:83], v[82:83], 0, v[160:161]
	v_mov_b32_e32 v84, v206
	v_mov_b32_e32 v85, v207
	v_mov_b32_e32 v86, v208
	v_mov_b32_e32 v87, v209
	s_nop 0
	v_lshlrev_b32_e32 v88, 16, v84
	v_and_b32_e32 v89, 0xffff0000, v84
	v_lshlrev_b32_e32 v84, 16, v85
	v_and_b32_e32 v85, 0xffff0000, v85
	v_pk_fma_f32 v[80:81], v[80:81], v[152:153], v[84:85]
	v_lshlrev_b32_e32 v84, 16, v86
	v_and_b32_e32 v85, 0xffff0000, v86
	v_pk_fma_f32 v[84:85], v[74:75], v[154:155], v[84:85]
	v_lshlrev_b32_e32 v74, 16, v87
	v_and_b32_e32 v75, 0xffff0000, v87
	v_pk_fma_f32 v[78:79], v[78:79], v[156:157], v[88:89]
	v_pk_fma_f32 v[86:87], v[76:77], v[150:151], v[74:75]
	v_cvt_pk_bf16_f32 v74, v78, v79
	v_cvt_pk_bf16_f32 v75, v80, v81
	v_cvt_pk_bf16_f32 v76, v84, v85
	v_cvt_pk_bf16_f32 v77, v86, v87
	global_store_dwordx4 v[82:83], v[74:77], off offset:2048
	s_nop 1
	v_mov_b32_e32 v74, v210
	v_mov_b32_e32 v75, v211
	v_mov_b32_e32 v76, v212
	v_mov_b32_e32 v77, v213
	s_nop 0
	v_lshlrev_b32_e32 v78, 16, v74
	v_and_b32_e32 v79, 0xffff0000, v74
	v_lshlrev_b32_e32 v74, 16, v75
	v_and_b32_e32 v75, 0xffff0000, v75
	v_pk_fma_f32 v[72:73], v[72:73], v[146:147], v[74:75]
	v_lshlrev_b32_e32 v74, 16, v76
	v_and_b32_e32 v75, 0xffff0000, v76
	v_pk_fma_f32 v[74:75], v[66:67], v[144:145], v[74:75]
	v_lshlrev_b32_e32 v66, 16, v77
	v_and_b32_e32 v67, 0xffff0000, v77
	v_pk_fma_f32 v[70:71], v[70:71], v[148:149], v[78:79]
	v_pk_fma_f32 v[76:77], v[68:69], v[142:143], v[66:67]
	v_cvt_pk_bf16_f32 v66, v70, v71
	v_cvt_pk_bf16_f32 v67, v72, v73
	v_cvt_pk_bf16_f32 v68, v74, v75
	v_cvt_pk_bf16_f32 v69, v76, v77
	v_lshl_add_u64 v[70:71], v[158:159], 0, s[14:15]
	global_store_dwordx4 v[82:83], v[66:69], off offset:2304
	s_nop 1
	v_mov_b32_e32 v66, v214
	v_mov_b32_e32 v67, v215
	v_mov_b32_e32 v68, v216
	v_mov_b32_e32 v69, v217
	s_mov_b64 s[14:15], 0x90000
	s_nop 0
	v_lshlrev_b32_e32 v72, 16, v66
	v_and_b32_e32 v73, 0xffff0000, v66
	v_lshlrev_b32_e32 v66, 16, v67
	v_and_b32_e32 v67, 0xffff0000, v67
	v_pk_fma_f32 v[64:65], v[64:65], v[152:153], v[66:67]
	v_lshlrev_b32_e32 v66, 16, v68
	v_and_b32_e32 v67, 0xffff0000, v68
	v_pk_fma_f32 v[66:67], v[58:59], v[154:155], v[66:67]
	v_lshlrev_b32_e32 v58, 16, v69
	v_and_b32_e32 v59, 0xffff0000, v69
	v_pk_fma_f32 v[62:63], v[62:63], v[156:157], v[72:73]
	v_pk_fma_f32 v[68:69], v[60:61], v[150:151], v[58:59]
	v_cvt_pk_bf16_f32 v58, v62, v63
	v_cvt_pk_bf16_f32 v59, v64, v65
	v_cvt_pk_bf16_f32 v60, v66, v67
	v_cvt_pk_bf16_f32 v61, v68, v69
	global_store_dwordx4 v[70:71], v[58:61], off offset:2048
	s_nop 1
	v_mov_b32_e32 v58, v218
	v_mov_b32_e32 v59, v219
	v_mov_b32_e32 v60, v220
	v_mov_b32_e32 v61, v221
	s_nop 0
	v_lshlrev_b32_e32 v62, 16, v58
	v_and_b32_e32 v63, 0xffff0000, v58
	v_lshlrev_b32_e32 v58, 16, v59
	v_and_b32_e32 v59, 0xffff0000, v59
	v_pk_fma_f32 v[56:57], v[56:57], v[146:147], v[58:59]
	v_lshlrev_b32_e32 v58, 16, v60
	v_and_b32_e32 v59, 0xffff0000, v60
	v_pk_fma_f32 v[58:59], v[50:51], v[144:145], v[58:59]
	v_lshlrev_b32_e32 v50, 16, v61
	v_and_b32_e32 v51, 0xffff0000, v61
	v_pk_fma_f32 v[54:55], v[54:55], v[148:149], v[62:63]
	v_pk_fma_f32 v[60:61], v[52:53], v[142:143], v[50:51]
	v_cvt_pk_bf16_f32 v50, v54, v55
	v_cvt_pk_bf16_f32 v51, v56, v57
	v_cvt_pk_bf16_f32 v52, v58, v59
	v_cvt_pk_bf16_f32 v53, v60, v61
	v_lshl_add_u64 v[54:55], v[158:159], 0, s[14:15]
	global_store_dwordx4 v[70:71], v[50:53], off offset:2304
	s_nop 1
	v_mov_b32_e32 v50, v222
	v_mov_b32_e32 v51, v223
	v_mov_b32_e32 v52, v224
	v_mov_b32_e32 v53, v225
	s_mov_b64 s[14:15], 0xa0000
	s_nop 0
	v_lshlrev_b32_e32 v56, 16, v50
	v_and_b32_e32 v57, 0xffff0000, v50
	v_lshlrev_b32_e32 v50, 16, v51
	v_and_b32_e32 v51, 0xffff0000, v51
	v_pk_fma_f32 v[48:49], v[48:49], v[152:153], v[50:51]
	v_lshlrev_b32_e32 v50, 16, v52
	v_and_b32_e32 v51, 0xffff0000, v52
	v_pk_fma_f32 v[50:51], v[42:43], v[154:155], v[50:51]
	v_lshlrev_b32_e32 v42, 16, v53
	v_and_b32_e32 v43, 0xffff0000, v53
	v_pk_fma_f32 v[46:47], v[46:47], v[156:157], v[56:57]
	v_pk_fma_f32 v[52:53], v[44:45], v[150:151], v[42:43]
	v_cvt_pk_bf16_f32 v42, v46, v47
	v_cvt_pk_bf16_f32 v43, v48, v49
	v_cvt_pk_bf16_f32 v44, v50, v51
	v_cvt_pk_bf16_f32 v45, v52, v53
	global_store_dwordx4 v[54:55], v[42:45], off offset:2048
	s_nop 1
	v_mov_b32_e32 v42, v226
	v_mov_b32_e32 v43, v227
	v_mov_b32_e32 v44, v228
	v_mov_b32_e32 v45, v229
	s_nop 0
	v_lshlrev_b32_e32 v46, 16, v42
	v_and_b32_e32 v47, 0xffff0000, v42
	v_lshlrev_b32_e32 v42, 16, v43
	v_and_b32_e32 v43, 0xffff0000, v43
	v_pk_fma_f32 v[40:41], v[40:41], v[146:147], v[42:43]
	v_lshlrev_b32_e32 v42, 16, v44
	v_and_b32_e32 v43, 0xffff0000, v44
	v_pk_fma_f32 v[42:43], v[34:35], v[144:145], v[42:43]
	v_lshlrev_b32_e32 v34, 16, v45
	v_and_b32_e32 v35, 0xffff0000, v45
	v_pk_fma_f32 v[38:39], v[38:39], v[148:149], v[46:47]
	v_pk_fma_f32 v[44:45], v[36:37], v[142:143], v[34:35]
	v_cvt_pk_bf16_f32 v34, v38, v39
	v_cvt_pk_bf16_f32 v35, v40, v41
	v_cvt_pk_bf16_f32 v36, v42, v43
	v_cvt_pk_bf16_f32 v37, v44, v45
	v_lshl_add_u64 v[38:39], v[158:159], 0, s[14:15]
	global_store_dwordx4 v[54:55], v[34:37], off offset:2304
	s_nop 1
	v_mov_b32_e32 v34, v230
	v_mov_b32_e32 v35, v231
	v_mov_b32_e32 v36, v232
	v_mov_b32_e32 v37, v233
	s_mov_b64 s[14:15], 0xb0000
	s_nop 0
	v_lshlrev_b32_e32 v40, 16, v34
	v_and_b32_e32 v41, 0xffff0000, v34
	v_lshlrev_b32_e32 v34, 16, v35
	v_and_b32_e32 v35, 0xffff0000, v35
	v_pk_fma_f32 v[32:33], v[32:33], v[152:153], v[34:35]
	v_lshlrev_b32_e32 v34, 16, v36
	v_and_b32_e32 v35, 0xffff0000, v36
	v_pk_fma_f32 v[34:35], v[26:27], v[154:155], v[34:35]
	v_lshlrev_b32_e32 v26, 16, v37
	v_and_b32_e32 v27, 0xffff0000, v37
	v_pk_fma_f32 v[30:31], v[30:31], v[156:157], v[40:41]
	v_pk_fma_f32 v[36:37], v[28:29], v[150:151], v[26:27]
	v_cvt_pk_bf16_f32 v26, v30, v31
	v_cvt_pk_bf16_f32 v27, v32, v33
	v_cvt_pk_bf16_f32 v28, v34, v35
	v_cvt_pk_bf16_f32 v29, v36, v37
	global_store_dwordx4 v[38:39], v[26:29], off offset:2048
	s_nop 1
	v_mov_b32_e32 v26, v236
	v_mov_b32_e32 v27, v237
	v_mov_b32_e32 v28, v238
	v_mov_b32_e32 v29, v239
	s_nop 0
	v_lshlrev_b32_e32 v30, 16, v26
	v_and_b32_e32 v31, 0xffff0000, v26
	v_lshlrev_b32_e32 v26, 16, v27
	v_and_b32_e32 v27, 0xffff0000, v27
	v_pk_fma_f32 v[24:25], v[24:25], v[146:147], v[26:27]
	v_lshlrev_b32_e32 v26, 16, v28
	v_and_b32_e32 v27, 0xffff0000, v28
	v_pk_fma_f32 v[26:27], v[18:19], v[144:145], v[26:27]
	v_lshlrev_b32_e32 v18, 16, v29
	v_and_b32_e32 v19, 0xffff0000, v29
	v_pk_fma_f32 v[22:23], v[22:23], v[148:149], v[30:31]
	v_pk_fma_f32 v[28:29], v[20:21], v[142:143], v[18:19]
	v_cvt_pk_bf16_f32 v18, v22, v23
	v_cvt_pk_bf16_f32 v19, v24, v25
	v_cvt_pk_bf16_f32 v20, v26, v27
	v_cvt_pk_bf16_f32 v21, v28, v29
	global_store_dwordx4 v[38:39], v[18:21], off offset:2304
	s_nop 1
	v_lshl_add_u64 v[18:19], v[158:159], 0, s[14:15]
	v_mov_b32_e32 v20, v246
	v_mov_b32_e32 v21, v247
	v_mov_b32_e32 v22, v248
	v_mov_b32_e32 v23, v249
	s_mov_b64 s[14:15], s[6:7]
	s_nop 0
	v_lshlrev_b32_e32 v24, 16, v20
	v_and_b32_e32 v25, 0xffff0000, v20
	v_lshlrev_b32_e32 v20, 16, v21
	v_and_b32_e32 v21, 0xffff0000, v21
	v_pk_fma_f32 v[16:17], v[16:17], v[152:153], v[20:21]
	v_lshlrev_b32_e32 v20, 16, v22
	v_and_b32_e32 v21, 0xffff0000, v22
	v_pk_fma_f32 v[20:21], v[10:11], v[154:155], v[20:21]
	v_lshlrev_b32_e32 v10, 16, v23
	v_and_b32_e32 v11, 0xffff0000, v23
	v_pk_fma_f32 v[14:15], v[14:15], v[156:157], v[24:25]
	v_pk_fma_f32 v[22:23], v[12:13], v[150:151], v[10:11]
	v_cvt_pk_bf16_f32 v10, v14, v15
	v_cvt_pk_bf16_f32 v11, v16, v17
	v_cvt_pk_bf16_f32 v12, v20, v21
	v_cvt_pk_bf16_f32 v13, v22, v23
	global_store_dwordx4 v[18:19], v[10:13], off offset:2048
	s_nop 1
	v_mov_b32_e32 v10, v250
	v_mov_b32_e32 v11, v251
	v_mov_b32_e32 v12, v252
	v_mov_b32_e32 v13, v253
	s_nop 0
	v_lshlrev_b32_e32 v14, 16, v10
	v_and_b32_e32 v15, 0xffff0000, v10
	v_lshlrev_b32_e32 v10, 16, v11
	v_and_b32_e32 v11, 0xffff0000, v11
	v_pk_fma_f32 v[8:9], v[8:9], v[146:147], v[10:11]
	v_lshlrev_b32_e32 v10, 16, v12
	v_and_b32_e32 v11, 0xffff0000, v12
	v_pk_fma_f32 v[10:11], v[2:3], v[144:145], v[10:11]
	v_lshlrev_b32_e32 v2, 16, v13
	v_and_b32_e32 v3, 0xffff0000, v13
	v_pk_fma_f32 v[6:7], v[6:7], v[148:149], v[14:15]
	v_pk_fma_f32 v[12:13], v[4:5], v[142:143], v[2:3]
	v_cvt_pk_bf16_f32 v2, v6, v7
	v_cvt_pk_bf16_f32 v3, v8, v9
	v_cvt_pk_bf16_f32 v4, v10, v11
	v_cvt_pk_bf16_f32 v5, v12, v13
	global_store_dwordx4 v[18:19], v[2:5], off offset:2304
	s_cbranch_vccz .LBB0_363
	s_waitcnt vmcnt(0)
	s_cmpk_gt_u32 s30, 0xff
	s_cbranch_scc1 .LBB0_378
	s_barrier

.LBB0_1408:
	s_add_u32 s16, s14, s6
	s_addc_u32 s17, s15, s7
	s_add_u32 s16, s16, 0x100
	s_addc_u32 s17, s17, 0
	s_add_u32 s48, s45, s6
	s_addc_u32 s49, s46, s7
	s_add_i32 s50, 0, 0x10000
	v_add_u32_e32 v158, s50, v164
	ds_read_b128 v[146:149], v158
	ds_read_b128 v[150:153], v158 offset:1024
	ds_read_b128 v[154:157], v158 offset:2048
	ds_read_b128 v[158:161], v158 offset:3072
	s_cmpk_eq_i32 s6, 0xf00
	s_cselect_b32 s19, s11, s17
	s_cselect_b32 s18, s10, s16
	s_cselect_b32 s17, s3, s49
	s_cselect_b32 s16, s44, s48
	v_lshl_add_u64 v[162:163], v[142:143], 0, s[6:7]
	s_add_i32 m0, s30, 0xc000
	ds_read_b128 v[168:171], v166
	ds_read_b128 v[172:175], v166 offset:1024
	ds_read_b128 v[186:189], v166 offset:2048
	ds_read_b128 v[190:193], v166 offset:3072
	ds_read_b128 v[194:197], v166 offset:4096
	ds_read_b128 v[198:201], v166 offset:5120
	ds_read_b128 v[202:205], v166 offset:6144
	ds_read_b128 v[206:209], v166 offset:7168
	global_load_lds_dwordx4 v[162:163], off
	v_lshl_add_u64 v[162:163], v[144:145], 0, s[6:7]
	s_add_i32 m0, s30, 0xe000
	s_nop 0
	global_load_lds_dwordx4 v[162:163], off
	s_waitcnt lgkmcnt(8)
	s_barrier
	s_waitcnt lgkmcnt(0)
	s_waitcnt lgkmcnt(0)
	v_mfma_f32_16x16x32_bf16 v[126:129], v[146:149], v[168:171], v[126:129]
	v_mfma_f32_16x16x32_bf16 v[122:125], v[154:157], v[168:171], v[122:125]
	v_mfma_f32_16x16x32_bf16 v[110:113], v[146:149], v[186:189], v[110:113]
	v_mfma_f32_16x16x32_bf16 v[106:109], v[154:157], v[186:189], v[106:109]
	v_mfma_f32_16x16x32_bf16 v[94:97], v[146:149], v[194:197], v[94:97]
	v_mfma_f32_16x16x32_bf16 v[90:93], v[154:157], v[194:197], v[90:93]
	v_mfma_f32_16x16x32_bf16 v[78:81], v[146:149], v[202:205], v[78:81]
	v_mfma_f32_16x16x32_bf16 v[74:77], v[154:157], v[202:205], v[74:77]
	v_mfma_f32_16x16x32_bf16 v[126:129], v[150:153], v[172:175], v[126:129]
	v_mfma_f32_16x16x32_bf16 v[122:125], v[158:161], v[172:175], v[122:125]
	v_mfma_f32_16x16x32_bf16 v[110:113], v[150:153], v[190:193], v[110:113]
	v_mfma_f32_16x16x32_bf16 v[106:109], v[158:161], v[190:193], v[106:109]
	v_mfma_f32_16x16x32_bf16 v[94:97], v[150:153], v[198:201], v[94:97]
	v_mfma_f32_16x16x32_bf16 v[90:93], v[158:161], v[198:201], v[90:93]
	v_mfma_f32_16x16x32_bf16 v[78:81], v[150:153], v[206:209], v[78:81]
	v_mfma_f32_16x16x32_bf16 v[74:77], v[158:161], v[206:209], v[74:77]
	s_barrier
	s_add_i32 s51, 0, 0x14000
	v_add_u32_e32 v162, s51, v164
	s_add_i32 s48, s50, s29
	ds_read_b128 v[210:213], v162
	ds_read_b128 v[214:217], v162 offset:1024
	ds_read_b128 v[218:221], v162 offset:2048
	ds_read_b128 v[222:225], v162 offset:3072
	s_add_u32 s64, s16, 0x80
	s_addc_u32 s65, s17, 0
	s_mov_b32 m0, s48
	s_nop 0
	global_load_lds_dwordx4 v132, s[16:17]
	s_add_i32 m0, s48, 0x2000
	s_nop 0
	global_load_lds_dwordx4 v136, s[16:17]
	s_barrier
	s_waitcnt lgkmcnt(0)
	s_waitcnt lgkmcnt(0)
	v_mfma_f32_16x16x32_bf16 v[118:121], v[210:213], v[168:171], v[118:121]
	v_mfma_f32_16x16x32_bf16 v[114:117], v[218:221], v[168:171], v[114:117]
	v_mfma_f32_16x16x32_bf16 v[102:105], v[210:213], v[186:189], v[102:105]
	v_mfma_f32_16x16x32_bf16 v[98:101], v[218:221], v[186:189], v[98:101]
	v_mfma_f32_16x16x32_bf16 v[86:89], v[210:213], v[194:197], v[86:89]
	v_mfma_f32_16x16x32_bf16 v[82:85], v[218:221], v[194:197], v[82:85]
	v_mfma_f32_16x16x32_bf16 v[70:73], v[210:213], v[202:205], v[70:73]
	v_mfma_f32_16x16x32_bf16 v[66:69], v[218:221], v[202:205], v[66:69]
	v_mfma_f32_16x16x32_bf16 v[118:121], v[214:217], v[172:175], v[118:121]
	v_mfma_f32_16x16x32_bf16 v[114:117], v[222:225], v[172:175], v[114:117]
	v_mfma_f32_16x16x32_bf16 v[102:105], v[214:217], v[190:193], v[102:105]
	v_mfma_f32_16x16x32_bf16 v[98:101], v[222:225], v[190:193], v[98:101]
	v_mfma_f32_16x16x32_bf16 v[86:89], v[214:217], v[198:201], v[86:89]
	v_mfma_f32_16x16x32_bf16 v[82:85], v[222:225], v[198:201], v[82:85]
	v_mfma_f32_16x16x32_bf16 v[70:73], v[214:217], v[206:209], v[70:73]
	v_mfma_f32_16x16x32_bf16 v[66:69], v[222:225], v[206:209], v[66:69]
	s_barrier
	s_mov_b32 m0, s30
	s_add_u32 s62, s18, 0x80
	s_addc_u32 s63, s19, 0
	ds_read_b128 v[168:171], v166 offset:16384
	ds_read_b128 v[172:175], v166 offset:17408
	ds_read_b128 v[186:189], v166 offset:18432
	ds_read_b128 v[190:193], v166 offset:19456
	ds_read_b128 v[194:197], v166 offset:20480
	ds_read_b128 v[198:201], v166 offset:21504
	ds_read_b128 v[202:205], v166 offset:22528
	ds_read_b128 v[206:209], v166 offset:23552
	global_load_lds_dwordx4 v130, s[18:19]
	s_mov_b32 m0, s31
	s_nop 0
	global_load_lds_dwordx4 v134, s[18:19]
	s_barrier
	s_waitcnt lgkmcnt(0)
	s_waitcnt lgkmcnt(0)
	v_mfma_f32_16x16x32_bf16 v[62:65], v[146:149], v[168:171], v[62:65]
	v_mfma_f32_16x16x32_bf16 v[58:61], v[154:157], v[168:171], v[58:61]
	v_mfma_f32_16x16x32_bf16 v[46:49], v[146:149], v[186:189], v[46:49]
	v_mfma_f32_16x16x32_bf16 v[42:45], v[154:157], v[186:189], v[42:45]
	v_mfma_f32_16x16x32_bf16 v[30:33], v[146:149], v[194:197], v[30:33]
	v_mfma_f32_16x16x32_bf16 v[26:29], v[154:157], v[194:197], v[26:29]
	v_mfma_f32_16x16x32_bf16 v[14:17], v[146:149], v[202:205], v[14:17]
	v_mfma_f32_16x16x32_bf16 v[10:13], v[154:157], v[202:205], v[10:13]
	v_mfma_f32_16x16x32_bf16 v[62:65], v[150:153], v[172:175], v[62:65]
	v_mfma_f32_16x16x32_bf16 v[58:61], v[158:161], v[172:175], v[58:61]
	v_mfma_f32_16x16x32_bf16 v[46:49], v[150:153], v[190:193], v[46:49]
	v_mfma_f32_16x16x32_bf16 v[42:45], v[158:161], v[190:193], v[42:45]
	v_mfma_f32_16x16x32_bf16 v[30:33], v[150:153], v[198:201], v[30:33]
	v_mfma_f32_16x16x32_bf16 v[26:29], v[158:161], v[198:201], v[26:29]
	v_mfma_f32_16x16x32_bf16 v[14:17], v[150:153], v[206:209], v[14:17]
	v_mfma_f32_16x16x32_bf16 v[10:13], v[158:161], v[206:209], v[10:13]
	s_barrier
	s_add_u32 s48, s16, 0x80000
	s_addc_u32 s49, s17, 0
	s_add_i32 s50, s51, s29
	s_mov_b32 m0, s50
	s_nop 0
	global_load_lds_dwordx4 v132, s[48:49]
	s_add_i32 m0, s50, 0x2000
	s_nop 0
	global_load_lds_dwordx4 v136, s[48:49]
	s_waitcnt vmcnt(6)
	s_barrier
	v_mfma_f32_16x16x32_bf16 v[54:57], v[210:213], v[168:171], v[54:57]
	v_mfma_f32_16x16x32_bf16 v[50:53], v[218:221], v[168:171], v[50:53]
	v_mfma_f32_16x16x32_bf16 v[38:41], v[210:213], v[186:189], v[38:41]
	v_mfma_f32_16x16x32_bf16 v[34:37], v[218:221], v[186:189], v[34:37]
	v_mfma_f32_16x16x32_bf16 v[22:25], v[210:213], v[194:197], v[22:25]
	v_mfma_f32_16x16x32_bf16 v[18:21], v[218:221], v[194:197], v[18:21]
	v_mfma_f32_16x16x32_bf16 v[6:9], v[210:213], v[202:205], v[6:9]
	v_mfma_f32_16x16x32_bf16 v[2:5], v[218:221], v[202:205], v[2:5]
	v_mfma_f32_16x16x32_bf16 v[54:57], v[214:217], v[172:175], v[54:57]
	v_mfma_f32_16x16x32_bf16 v[50:53], v[222:225], v[172:175], v[50:53]
	v_mfma_f32_16x16x32_bf16 v[38:41], v[214:217], v[190:193], v[38:41]
	v_mfma_f32_16x16x32_bf16 v[34:37], v[222:225], v[190:193], v[34:37]
	v_mfma_f32_16x16x32_bf16 v[22:25], v[214:217], v[198:201], v[22:25]
	v_mfma_f32_16x16x32_bf16 v[18:21], v[222:225], v[198:201], v[18:21]
	v_mfma_f32_16x16x32_bf16 v[6:9], v[214:217], v[206:209], v[6:9]
	v_mfma_f32_16x16x32_bf16 v[2:5], v[222:225], v[206:209], v[2:5]
	s_barrier
	s_add_i32 s48, 0, 0x18000
	v_add_u32_e32 v158, s48, v164
	ds_read_b128 v[146:149], v158
	ds_read_b128 v[150:153], v158 offset:1024
	ds_read_b128 v[154:157], v158 offset:2048
	ds_read_b128 v[158:161], v158 offset:3072
	s_add_u32 s18, s18, s80
	s_addc_u32 s19, s19, 0
	s_mov_b32 m0, s34
	ds_read_b128 v[168:171], v166 offset:32768
	ds_read_b128 v[172:175], v166 offset:33792
	ds_read_b128 v[186:189], v166 offset:34816
	ds_read_b128 v[190:193], v166 offset:35840
	ds_read_b128 v[194:197], v166 offset:36864
	ds_read_b128 v[198:201], v166 offset:37888
	ds_read_b128 v[202:205], v166 offset:38912
	ds_read_b128 v[206:209], v166 offset:39936
	global_load_lds_dwordx4 v130, s[18:19]
	s_mov_b32 m0, s35
	s_nop 0
	global_load_lds_dwordx4 v134, s[18:19]
	s_waitcnt lgkmcnt(8)
	s_barrier
	s_waitcnt lgkmcnt(0)
	s_waitcnt lgkmcnt(0)
	v_mfma_f32_16x16x32_bf16 v[126:129], v[146:149], v[168:171], v[126:129]
	v_mfma_f32_16x16x32_bf16 v[122:125], v[154:157], v[168:171], v[122:125]
	v_mfma_f32_16x16x32_bf16 v[110:113], v[146:149], v[186:189], v[110:113]
	v_mfma_f32_16x16x32_bf16 v[106:109], v[154:157], v[186:189], v[106:109]
	v_mfma_f32_16x16x32_bf16 v[94:97], v[146:149], v[194:197], v[94:97]
	v_mfma_f32_16x16x32_bf16 v[90:93], v[154:157], v[194:197], v[90:93]
	v_mfma_f32_16x16x32_bf16 v[78:81], v[146:149], v[202:205], v[78:81]
	v_mfma_f32_16x16x32_bf16 v[74:77], v[154:157], v[202:205], v[74:77]
	v_mfma_f32_16x16x32_bf16 v[126:129], v[150:153], v[172:175], v[126:129]
	v_mfma_f32_16x16x32_bf16 v[122:125], v[158:161], v[172:175], v[122:125]
	v_mfma_f32_16x16x32_bf16 v[110:113], v[150:153], v[190:193], v[110:113]
	v_mfma_f32_16x16x32_bf16 v[106:109], v[158:161], v[190:193], v[106:109]
	v_mfma_f32_16x16x32_bf16 v[94:97], v[150:153], v[198:201], v[94:97]
	v_mfma_f32_16x16x32_bf16 v[90:93], v[158:161], v[198:201], v[90:93]
	v_mfma_f32_16x16x32_bf16 v[78:81], v[150:153], v[206:209], v[78:81]
	v_mfma_f32_16x16x32_bf16 v[74:77], v[158:161], v[206:209], v[74:77]
	s_barrier
	s_add_i32 s18, 0, 0x1c000
	s_add_i32 s19, s48, s29
	v_add_u32_e32 v167, s18, v164
	s_mov_b32 m0, s19
	ds_read_b128 v[210:213], v167
	ds_read_b128 v[214:217], v167 offset:1024
	ds_read_b128 v[218:221], v167 offset:2048
	ds_read_b128 v[222:225], v167 offset:3072
	global_load_lds_dwordx4 v132, s[64:65]
	s_add_i32 m0, s19, 0x2000
	s_nop 0
	global_load_lds_dwordx4 v136, s[64:65]
	s_barrier
	s_waitcnt lgkmcnt(0)
	s_waitcnt lgkmcnt(0)
	v_mfma_f32_16x16x32_bf16 v[118:121], v[210:213], v[168:171], v[118:121]
	v_mfma_f32_16x16x32_bf16 v[114:117], v[218:221], v[168:171], v[114:117]
	v_mfma_f32_16x16x32_bf16 v[102:105], v[210:213], v[186:189], v[102:105]
	v_mfma_f32_16x16x32_bf16 v[98:101], v[218:221], v[186:189], v[98:101]
	v_mfma_f32_16x16x32_bf16 v[86:89], v[210:213], v[194:197], v[86:89]
	v_mfma_f32_16x16x32_bf16 v[82:85], v[218:221], v[194:197], v[82:85]
	v_mfma_f32_16x16x32_bf16 v[70:73], v[210:213], v[202:205], v[70:73]
	v_mfma_f32_16x16x32_bf16 v[66:69], v[218:221], v[202:205], v[66:69]
	v_mfma_f32_16x16x32_bf16 v[118:121], v[214:217], v[172:175], v[118:121]
	v_mfma_f32_16x16x32_bf16 v[114:117], v[222:225], v[172:175], v[114:117]
	v_mfma_f32_16x16x32_bf16 v[102:105], v[214:217], v[190:193], v[102:105]
	v_mfma_f32_16x16x32_bf16 v[98:101], v[222:225], v[190:193], v[98:101]
	v_mfma_f32_16x16x32_bf16 v[86:89], v[214:217], v[198:201], v[86:89]
	v_mfma_f32_16x16x32_bf16 v[82:85], v[222:225], v[198:201], v[82:85]
	v_mfma_f32_16x16x32_bf16 v[70:73], v[214:217], v[206:209], v[70:73]
	v_mfma_f32_16x16x32_bf16 v[66:69], v[222:225], v[206:209], v[66:69]
	s_barrier
	s_mov_b32 m0, s38
	ds_read_b128 v[168:171], v166 offset:49152
	ds_read_b128 v[172:175], v166 offset:50176
	ds_read_b128 v[186:189], v166 offset:51200
	ds_read_b128 v[190:193], v166 offset:52224
	ds_read_b128 v[194:197], v166 offset:53248
	ds_read_b128 v[198:201], v166 offset:54272
	ds_read_b128 v[202:205], v166 offset:55296
	ds_read_b128 v[206:209], v166 offset:56320
	global_load_lds_dwordx4 v130, s[62:63]
	s_mov_b32 m0, s39
	s_nop 0
	global_load_lds_dwordx4 v134, s[62:63]
	s_barrier
	s_waitcnt lgkmcnt(0)
	s_waitcnt lgkmcnt(0)
	v_mfma_f32_16x16x32_bf16 v[62:65], v[146:149], v[168:171], v[62:65]
	v_mfma_f32_16x16x32_bf16 v[58:61], v[154:157], v[168:171], v[58:61]
	v_mfma_f32_16x16x32_bf16 v[46:49], v[146:149], v[186:189], v[46:49]
	v_mfma_f32_16x16x32_bf16 v[42:45], v[154:157], v[186:189], v[42:45]
	v_mfma_f32_16x16x32_bf16 v[30:33], v[146:149], v[194:197], v[30:33]
	v_mfma_f32_16x16x32_bf16 v[26:29], v[154:157], v[194:197], v[26:29]
	v_mfma_f32_16x16x32_bf16 v[14:17], v[146:149], v[202:205], v[14:17]
	v_mfma_f32_16x16x32_bf16 v[10:13], v[154:157], v[202:205], v[10:13]
	v_mfma_f32_16x16x32_bf16 v[62:65], v[150:153], v[172:175], v[62:65]
	v_mfma_f32_16x16x32_bf16 v[58:61], v[158:161], v[172:175], v[58:61]
	v_mfma_f32_16x16x32_bf16 v[46:49], v[150:153], v[190:193], v[46:49]
	v_mfma_f32_16x16x32_bf16 v[42:45], v[158:161], v[190:193], v[42:45]
	v_mfma_f32_16x16x32_bf16 v[30:33], v[150:153], v[198:201], v[30:33]
	v_mfma_f32_16x16x32_bf16 v[26:29], v[158:161], v[198:201], v[26:29]
	v_mfma_f32_16x16x32_bf16 v[14:17], v[150:153], v[206:209], v[14:17]
	v_mfma_f32_16x16x32_bf16 v[10:13], v[158:161], v[206:209], v[10:13]
	s_barrier
	s_add_u32 s16, s16, 0x80080
	s_addc_u32 s17, s17, 0
	s_add_i32 s18, s18, s29
	s_mov_b32 m0, s18
	s_nop 0
	global_load_lds_dwordx4 v132, s[16:17]
	s_add_i32 m0, s18, 0x2000
	s_nop 0
	global_load_lds_dwordx4 v136, s[16:17]
	s_waitcnt vmcnt(6)
	s_barrier
	v_mfma_f32_16x16x32_bf16 v[54:57], v[210:213], v[168:171], v[54:57]
	v_mfma_f32_16x16x32_bf16 v[50:53], v[218:221], v[168:171], v[50:53]
	v_mfma_f32_16x16x32_bf16 v[38:41], v[210:213], v[186:189], v[38:41]
	v_mfma_f32_16x16x32_bf16 v[34:37], v[218:221], v[186:189], v[34:37]
	v_mfma_f32_16x16x32_bf16 v[22:25], v[210:213], v[194:197], v[22:25]
	v_mfma_f32_16x16x32_bf16 v[18:21], v[218:221], v[194:197], v[18:21]
	v_mfma_f32_16x16x32_bf16 v[6:9], v[210:213], v[202:205], v[6:9]
	v_mfma_f32_16x16x32_bf16 v[2:5], v[218:221], v[202:205], v[2:5]
	v_mfma_f32_16x16x32_bf16 v[54:57], v[214:217], v[172:175], v[54:57]
	v_mfma_f32_16x16x32_bf16 v[50:53], v[222:225], v[172:175], v[50:53]
	v_mfma_f32_16x16x32_bf16 v[38:41], v[214:217], v[190:193], v[38:41]
	v_mfma_f32_16x16x32_bf16 v[34:37], v[222:225], v[190:193], v[34:37]
	v_mfma_f32_16x16x32_bf16 v[22:25], v[214:217], v[198:201], v[22:25]
	v_mfma_f32_16x16x32_bf16 v[18:21], v[222:225], v[198:201], v[18:21]
	v_mfma_f32_16x16x32_bf16 v[6:9], v[214:217], v[206:209], v[6:9]
	v_mfma_f32_16x16x32_bf16 v[2:5], v[222:225], v[206:209], v[2:5]
	s_barrier
	s_add_i32 s47, s47, 2
	s_add_u32 s6, s6, 0x100
	s_addc_u32 s7, s7, 0
	s_cmp_gt_u32 s47, 29
	s_cbranch_scc0 .LBB0_1408
	s_ashr_i32 s3, s33, 5
	s_mul_hi_i32 s7, s3, 0x9000
	s_mul_i32 s3, s3, 0x9000
	v_lshl_or_b32 v168, s43, 8, v165
	s_add_u32 s6, s36, s3
	s_addc_u32 s7, s37, s7
	v_ashrrev_i32_e32 v169, 31, v168
	v_lshl_add_u64 v[162:163], v[168:169], 2, s[6:7]
	global_load_dwordx4 v[142:145], v[162:163], off offset:16
	global_load_dwordx4 v[146:149], v[162:163], off
	s_mov_b64 s[6:7], 0x80000
	s_and_b64 vcc, exec, s[4:5]
	s_mov_b32 s43, s2
	s_mov_b64 s[16:17], s[12:13]
	s_mov_b64 s[14:15], s[10:11]
	s_waitcnt vmcnt(0)
	v_pk_add_f32 v[150:151], v[144:145], 1.0 op_sel_hi:[1,0]
	v_pk_add_f32 v[154:155], v[142:143], 1.0 op_sel_hi:[1,0]
	global_load_dwordx4 v[158:161], v[162:163], off offset:528
	global_load_dwordx4 v[142:145], v[162:163], off offset:512
	v_lshl_add_u32 v162, s33, 8, v1
	v_ashrrev_i32_e32 v163, 31, v162
	v_lshlrev_b64 v[152:153], 12, v[162:163]
	v_lshl_add_u64 v[152:153], s[8:9], 0, v[152:153]
	v_lshl_add_u64 v[152:153], v[168:169], 1, v[152:153]
	v_mov_b32_e32 v156, 0x10000
	v_mov_b32_e32 v157, 0
	global_load_dwordx4 v[174:177], v[152:153], off offset:2048
	global_load_dwordx4 v[186:189], v[152:153], off offset:2304
	v_lshl_add_u64 v[152:153], v[152:153], 0, v[156:157]
	global_load_dwordx4 v[190:193], v[152:153], off offset:2048
	global_load_dwordx4 v[194:197], v[152:153], off offset:2304
	v_lshl_add_u64 v[152:153], v[152:153], 0, v[156:157]
	global_load_dwordx4 v[198:201], v[152:153], off offset:2048
	global_load_dwordx4 v[202:205], v[152:153], off offset:2304
	v_lshl_add_u64 v[152:153], v[152:153], 0, v[156:157]
	global_load_dwordx4 v[206:209], v[152:153], off offset:2048
	global_load_dwordx4 v[210:213], v[152:153], off offset:2304
	v_mov_b32_e32 v156, 0x50000
	v_lshl_add_u64 v[152:153], v[152:153], 0, v[156:157]
	v_mov_b32_e32 v156, 0x10000
	global_load_dwordx4 v[214:217], v[152:153], off offset:2048
	global_load_dwordx4 v[218:221], v[152:153], off offset:2304
	v_lshl_add_u64 v[152:153], v[152:153], 0, v[156:157]
	global_load_dwordx4 v[222:225], v[152:153], off offset:2048
	global_load_dwordx4 v[226:229], v[152:153], off offset:2304
	v_lshl_add_u64 v[152:153], v[152:153], 0, v[156:157]
	global_load_dwordx4 v[230:233], v[152:153], off offset:2048
	global_load_dwordx4 v[236:239], v[152:153], off offset:2304
	v_lshl_add_u64 v[152:153], v[152:153], 0, v[156:157]
	global_load_dwordx4 v[246:249], v[152:153], off offset:2048
	global_load_dwordx4 v[250:253], v[152:153], off offset:2304
	v_pk_add_f32 v[156:157], v[146:147], 1.0 op_sel_hi:[1,0]
	v_pk_add_f32 v[152:153], v[148:149], 1.0 op_sel_hi:[1,0]
	s_mov_b32 s33, s42
	s_waitcnt vmcnt(0)
	v_pk_add_f32 v[146:147], v[144:145], 1.0 op_sel_hi:[1,0]
	v_pk_add_f32 v[144:145], v[158:159], 1.0 op_sel_hi:[1,0]
	v_lshlrev_b64 v[158:159], 12, v[162:163]
	v_pk_add_f32 v[148:149], v[142:143], 1.0 op_sel_hi:[1,0]
	v_pk_add_f32 v[142:143], v[160:161], 1.0 op_sel_hi:[1,0]
	v_lshl_add_u64 v[158:159], s[8:9], 0, v[158:159]
	v_lshlrev_b64 v[160:161], 1, v[168:169]
	v_lshl_add_u64 v[158:159], v[158:159], 0, v[160:161]
	v_mov_b32_e32 v168, v174
	v_mov_b32_e32 v169, v175
	v_mov_b32_e32 v170, v176
	v_mov_b32_e32 v171, v177
	s_nop 0
	v_lshlrev_b32_e32 v172, 16, v168
	v_and_b32_e32 v173, 0xffff0000, v168
	v_lshlrev_b32_e32 v168, 16, v169
	v_and_b32_e32 v169, 0xffff0000, v169
	v_pk_fma_f32 v[128:129], v[128:129], v[152:153], v[168:169]
	v_lshlrev_b32_e32 v168, 16, v170
	v_and_b32_e32 v169, 0xffff0000, v170
	v_pk_fma_f32 v[168:169], v[122:123], v[154:155], v[168:169]
	v_lshlrev_b32_e32 v122, 16, v171
	v_and_b32_e32 v123, 0xffff0000, v171
	v_pk_fma_f32 v[126:127], v[126:127], v[156:157], v[172:173]
	v_pk_fma_f32 v[170:171], v[124:125], v[150:151], v[122:123]
	v_cvt_pk_bf16_f32 v122, v126, v127
	v_cvt_pk_bf16_f32 v123, v128, v129
	v_cvt_pk_bf16_f32 v124, v168, v169
	v_cvt_pk_bf16_f32 v125, v170, v171
	global_store_dwordx4 v[158:159], v[122:125], off offset:2048
	s_nop 1
	v_mov_b32_e32 v122, v186
	v_mov_b32_e32 v123, v187
	v_mov_b32_e32 v124, v188
	v_mov_b32_e32 v125, v189
	s_nop 0
	v_lshlrev_b32_e32 v126, 16, v122
	v_and_b32_e32 v127, 0xffff0000, v122
	v_lshlrev_b32_e32 v122, 16, v123
	v_and_b32_e32 v123, 0xffff0000, v123
	v_pk_fma_f32 v[120:121], v[120:121], v[146:147], v[122:123]
	v_lshlrev_b32_e32 v122, 16, v124
	v_and_b32_e32 v123, 0xffff0000, v124
	v_pk_fma_f32 v[122:123], v[114:115], v[144:145], v[122:123]
	v_lshlrev_b32_e32 v114, 16, v125
	v_and_b32_e32 v115, 0xffff0000, v125
	v_pk_fma_f32 v[118:119], v[118:119], v[148:149], v[126:127]
	v_pk_fma_f32 v[124:125], v[116:117], v[142:143], v[114:115]
	v_cvt_pk_bf16_f32 v114, v118, v119
	v_cvt_pk_bf16_f32 v115, v120, v121
	v_cvt_pk_bf16_f32 v116, v122, v123
	v_cvt_pk_bf16_f32 v117, v124, v125
	global_store_dwordx4 v[158:159], v[114:117], off offset:2304
	s_nop 1
	v_or_b32_e32 v114, 16, v162
	v_ashrrev_i32_e32 v115, 31, v114
	v_lshlrev_b64 v[114:115], 12, v[114:115]
	v_lshl_add_u64 v[114:115], s[8:9], 0, v[114:115]
	v_lshl_add_u64 v[118:119], v[114:115], 0, v[160:161]
	v_mov_b32_e32 v114, v190
	v_mov_b32_e32 v115, v191
	v_mov_b32_e32 v116, v192
	v_mov_b32_e32 v117, v193
	s_nop 0
	v_lshlrev_b32_e32 v120, 16, v114
	v_and_b32_e32 v121, 0xffff0000, v114
	v_lshlrev_b32_e32 v114, 16, v115
	v_and_b32_e32 v115, 0xffff0000, v115
	v_pk_fma_f32 v[112:113], v[112:113], v[152:153], v[114:115]
	v_lshlrev_b32_e32 v114, 16, v116
	v_and_b32_e32 v115, 0xffff0000, v116
	v_pk_fma_f32 v[114:115], v[106:107], v[154:155], v[114:115]
	v_lshlrev_b32_e32 v106, 16, v117
	v_and_b32_e32 v107, 0xffff0000, v117
	v_pk_fma_f32 v[110:111], v[110:111], v[156:157], v[120:121]
	v_pk_fma_f32 v[116:117], v[108:109], v[150:151], v[106:107]
	v_cvt_pk_bf16_f32 v106, v110, v111
	v_cvt_pk_bf16_f32 v107, v112, v113
	v_cvt_pk_bf16_f32 v108, v114, v115
	v_cvt_pk_bf16_f32 v109, v116, v117
	global_store_dwordx4 v[118:119], v[106:109], off offset:2048
	s_nop 1
	v_mov_b32_e32 v106, v194
	v_mov_b32_e32 v107, v195
	v_mov_b32_e32 v108, v196
	v_mov_b32_e32 v109, v197
	s_nop 0
	v_lshlrev_b32_e32 v110, 16, v106
	v_and_b32_e32 v111, 0xffff0000, v106
	v_lshlrev_b32_e32 v106, 16, v107
	v_and_b32_e32 v107, 0xffff0000, v107
	v_pk_fma_f32 v[104:105], v[104:105], v[146:147], v[106:107]
	v_lshlrev_b32_e32 v106, 16, v108
	v_and_b32_e32 v107, 0xffff0000, v108
	v_pk_fma_f32 v[106:107], v[98:99], v[144:145], v[106:107]
	v_lshlrev_b32_e32 v98, 16, v109
	v_and_b32_e32 v99, 0xffff0000, v109
	v_pk_fma_f32 v[102:103], v[102:103], v[148:149], v[110:111]
	v_pk_fma_f32 v[108:109], v[100:101], v[142:143], v[98:99]
	v_cvt_pk_bf16_f32 v98, v102, v103
	v_cvt_pk_bf16_f32 v99, v104, v105
	v_cvt_pk_bf16_f32 v100, v106, v107
	v_cvt_pk_bf16_f32 v101, v108, v109
	global_store_dwordx4 v[118:119], v[98:101], off offset:2304
	s_nop 1
	v_or_b32_e32 v98, 32, v162
	v_ashrrev_i32_e32 v99, 31, v98
	v_lshlrev_b64 v[98:99], 12, v[98:99]
	v_lshl_add_u64 v[98:99], s[8:9], 0, v[98:99]
	v_lshl_add_u64 v[102:103], v[98:99], 0, v[160:161]
	v_mov_b32_e32 v98, v198
	v_mov_b32_e32 v99, v199
	v_mov_b32_e32 v100, v200
	v_mov_b32_e32 v101, v201
	s_nop 0
	v_lshlrev_b32_e32 v104, 16, v98
	v_and_b32_e32 v105, 0xffff0000, v98
	v_lshlrev_b32_e32 v98, 16, v99
	v_and_b32_e32 v99, 0xffff0000, v99
	v_pk_fma_f32 v[96:97], v[96:97], v[152:153], v[98:99]
	v_lshlrev_b32_e32 v98, 16, v100
	v_and_b32_e32 v99, 0xffff0000, v100
	v_pk_fma_f32 v[98:99], v[90:91], v[154:155], v[98:99]
	v_lshlrev_b32_e32 v90, 16, v101
	v_and_b32_e32 v91, 0xffff0000, v101
	v_pk_fma_f32 v[94:95], v[94:95], v[156:157], v[104:105]
	v_pk_fma_f32 v[100:101], v[92:93], v[150:151], v[90:91]
	v_cvt_pk_bf16_f32 v90, v94, v95
	v_cvt_pk_bf16_f32 v91, v96, v97
	v_cvt_pk_bf16_f32 v92, v98, v99
	v_cvt_pk_bf16_f32 v93, v100, v101
	global_store_dwordx4 v[102:103], v[90:93], off offset:2048
	s_nop 1
	v_mov_b32_e32 v90, v202
	v_mov_b32_e32 v91, v203
	v_mov_b32_e32 v92, v204
	v_mov_b32_e32 v93, v205
	s_nop 0
	v_lshlrev_b32_e32 v94, 16, v90
	v_and_b32_e32 v95, 0xffff0000, v90
	v_lshlrev_b32_e32 v90, 16, v91
	v_and_b32_e32 v91, 0xffff0000, v91
	v_pk_fma_f32 v[88:89], v[88:89], v[146:147], v[90:91]
	v_lshlrev_b32_e32 v90, 16, v92
	v_and_b32_e32 v91, 0xffff0000, v92
	v_pk_fma_f32 v[90:91], v[82:83], v[144:145], v[90:91]
	v_lshlrev_b32_e32 v82, 16, v93
	v_and_b32_e32 v83, 0xffff0000, v93
	v_pk_fma_f32 v[86:87], v[86:87], v[148:149], v[94:95]
	v_pk_fma_f32 v[92:93], v[84:85], v[142:143], v[82:83]
	v_cvt_pk_bf16_f32 v82, v86, v87
	v_cvt_pk_bf16_f32 v83, v88, v89
	v_cvt_pk_bf16_f32 v84, v90, v91
	v_cvt_pk_bf16_f32 v85, v92, v93
	global_store_dwordx4 v[102:103], v[82:85], off offset:2304
	s_nop 1
	v_or_b32_e32 v82, 48, v162
	v_ashrrev_i32_e32 v83, 31, v82
	v_lshlrev_b64 v[82:83], 12, v[82:83]
	v_lshl_add_u64 v[82:83], s[8:9], 0, v[82:83]
	v_lshl_add_u64 v[82:83], v[82:83], 0, v[160:161]
	v_mov_b32_e32 v84, v206
	v_mov_b32_e32 v85, v207
	v_mov_b32_e32 v86, v208
	v_mov_b32_e32 v87, v209
	s_nop 0
	v_lshlrev_b32_e32 v88, 16, v84
	v_and_b32_e32 v89, 0xffff0000, v84
	v_lshlrev_b32_e32 v84, 16, v85
	v_and_b32_e32 v85, 0xffff0000, v85
	v_pk_fma_f32 v[80:81], v[80:81], v[152:153], v[84:85]
	v_lshlrev_b32_e32 v84, 16, v86
	v_and_b32_e32 v85, 0xffff0000, v86
	v_pk_fma_f32 v[84:85], v[74:75], v[154:155], v[84:85]
	v_lshlrev_b32_e32 v74, 16, v87
	v_and_b32_e32 v75, 0xffff0000, v87
	v_pk_fma_f32 v[78:79], v[78:79], v[156:157], v[88:89]
	v_pk_fma_f32 v[86:87], v[76:77], v[150:151], v[74:75]
	v_cvt_pk_bf16_f32 v74, v78, v79
	v_cvt_pk_bf16_f32 v75, v80, v81
	v_cvt_pk_bf16_f32 v76, v84, v85
	v_cvt_pk_bf16_f32 v77, v86, v87
	global_store_dwordx4 v[82:83], v[74:77], off offset:2048
	s_nop 1
	v_mov_b32_e32 v74, v210
	v_mov_b32_e32 v75, v211
	v_mov_b32_e32 v76, v212
	v_mov_b32_e32 v77, v213
	s_nop 0
	v_lshlrev_b32_e32 v78, 16, v74
	v_and_b32_e32 v79, 0xffff0000, v74
	v_lshlrev_b32_e32 v74, 16, v75
	v_and_b32_e32 v75, 0xffff0000, v75
	v_pk_fma_f32 v[72:73], v[72:73], v[146:147], v[74:75]
	v_lshlrev_b32_e32 v74, 16, v76
	v_and_b32_e32 v75, 0xffff0000, v76
	v_pk_fma_f32 v[74:75], v[66:67], v[144:145], v[74:75]
	v_lshlrev_b32_e32 v66, 16, v77
	v_and_b32_e32 v67, 0xffff0000, v77
	v_pk_fma_f32 v[70:71], v[70:71], v[148:149], v[78:79]
	v_pk_fma_f32 v[76:77], v[68:69], v[142:143], v[66:67]
	v_cvt_pk_bf16_f32 v66, v70, v71
	v_cvt_pk_bf16_f32 v67, v72, v73
	v_cvt_pk_bf16_f32 v68, v74, v75
	v_cvt_pk_bf16_f32 v69, v76, v77
	v_lshl_add_u64 v[70:71], v[158:159], 0, s[6:7]
	global_store_dwordx4 v[82:83], v[66:69], off offset:2304
	s_nop 1
	v_mov_b32_e32 v66, v214
	v_mov_b32_e32 v67, v215
	v_mov_b32_e32 v68, v216
	v_mov_b32_e32 v69, v217
	s_mov_b64 s[6:7], 0x90000
	s_nop 0
	v_lshlrev_b32_e32 v72, 16, v66
	v_and_b32_e32 v73, 0xffff0000, v66
	v_lshlrev_b32_e32 v66, 16, v67
	v_and_b32_e32 v67, 0xffff0000, v67
	v_pk_fma_f32 v[64:65], v[64:65], v[152:153], v[66:67]
	v_lshlrev_b32_e32 v66, 16, v68
	v_and_b32_e32 v67, 0xffff0000, v68
	v_pk_fma_f32 v[66:67], v[58:59], v[154:155], v[66:67]
	v_lshlrev_b32_e32 v58, 16, v69
	v_and_b32_e32 v59, 0xffff0000, v69
	v_pk_fma_f32 v[62:63], v[62:63], v[156:157], v[72:73]
	v_pk_fma_f32 v[68:69], v[60:61], v[150:151], v[58:59]
	v_cvt_pk_bf16_f32 v58, v62, v63
	v_cvt_pk_bf16_f32 v59, v64, v65
	v_cvt_pk_bf16_f32 v60, v66, v67
	v_cvt_pk_bf16_f32 v61, v68, v69
	global_store_dwordx4 v[70:71], v[58:61], off offset:2048
	s_nop 1
	v_mov_b32_e32 v58, v218
	v_mov_b32_e32 v59, v219
	v_mov_b32_e32 v60, v220
	v_mov_b32_e32 v61, v221
	s_nop 0
	v_lshlrev_b32_e32 v62, 16, v58
	v_and_b32_e32 v63, 0xffff0000, v58
	v_lshlrev_b32_e32 v58, 16, v59
	v_and_b32_e32 v59, 0xffff0000, v59
	v_pk_fma_f32 v[56:57], v[56:57], v[146:147], v[58:59]
	v_lshlrev_b32_e32 v58, 16, v60
	v_and_b32_e32 v59, 0xffff0000, v60
	v_pk_fma_f32 v[58:59], v[50:51], v[144:145], v[58:59]
	v_lshlrev_b32_e32 v50, 16, v61
	v_and_b32_e32 v51, 0xffff0000, v61
	v_pk_fma_f32 v[54:55], v[54:55], v[148:149], v[62:63]
	v_pk_fma_f32 v[60:61], v[52:53], v[142:143], v[50:51]
	v_cvt_pk_bf16_f32 v50, v54, v55
	v_cvt_pk_bf16_f32 v51, v56, v57
	v_cvt_pk_bf16_f32 v52, v58, v59
	v_cvt_pk_bf16_f32 v53, v60, v61
	v_lshl_add_u64 v[54:55], v[158:159], 0, s[6:7]
	global_store_dwordx4 v[70:71], v[50:53], off offset:2304
	s_nop 1
	v_mov_b32_e32 v50, v222
	v_mov_b32_e32 v51, v223
	v_mov_b32_e32 v52, v224
	v_mov_b32_e32 v53, v225
	s_mov_b64 s[6:7], 0xa0000
	s_nop 0
	v_lshlrev_b32_e32 v56, 16, v50
	v_and_b32_e32 v57, 0xffff0000, v50
	v_lshlrev_b32_e32 v50, 16, v51
	v_and_b32_e32 v51, 0xffff0000, v51
	v_pk_fma_f32 v[48:49], v[48:49], v[152:153], v[50:51]
	v_lshlrev_b32_e32 v50, 16, v52
	v_and_b32_e32 v51, 0xffff0000, v52
	v_pk_fma_f32 v[50:51], v[42:43], v[154:155], v[50:51]
	v_lshlrev_b32_e32 v42, 16, v53
	v_and_b32_e32 v43, 0xffff0000, v53
	v_pk_fma_f32 v[46:47], v[46:47], v[156:157], v[56:57]
	v_pk_fma_f32 v[52:53], v[44:45], v[150:151], v[42:43]
	v_cvt_pk_bf16_f32 v42, v46, v47
	v_cvt_pk_bf16_f32 v43, v48, v49
	v_cvt_pk_bf16_f32 v44, v50, v51
	v_cvt_pk_bf16_f32 v45, v52, v53
	global_store_dwordx4 v[54:55], v[42:45], off offset:2048
	s_nop 1
	v_mov_b32_e32 v42, v226
	v_mov_b32_e32 v43, v227
	v_mov_b32_e32 v44, v228
	v_mov_b32_e32 v45, v229
	s_nop 0
	v_lshlrev_b32_e32 v46, 16, v42
	v_and_b32_e32 v47, 0xffff0000, v42
	v_lshlrev_b32_e32 v42, 16, v43
	v_and_b32_e32 v43, 0xffff0000, v43
	v_pk_fma_f32 v[40:41], v[40:41], v[146:147], v[42:43]
	v_lshlrev_b32_e32 v42, 16, v44
	v_and_b32_e32 v43, 0xffff0000, v44
	v_pk_fma_f32 v[42:43], v[34:35], v[144:145], v[42:43]
	v_lshlrev_b32_e32 v34, 16, v45
	v_and_b32_e32 v35, 0xffff0000, v45
	v_pk_fma_f32 v[38:39], v[38:39], v[148:149], v[46:47]
	v_pk_fma_f32 v[44:45], v[36:37], v[142:143], v[34:35]
	v_cvt_pk_bf16_f32 v34, v38, v39
	v_cvt_pk_bf16_f32 v35, v40, v41
	v_cvt_pk_bf16_f32 v36, v42, v43
	v_cvt_pk_bf16_f32 v37, v44, v45
	v_lshl_add_u64 v[38:39], v[158:159], 0, s[6:7]
	global_store_dwordx4 v[54:55], v[34:37], off offset:2304
	s_nop 1
	v_mov_b32_e32 v34, v230
	v_mov_b32_e32 v35, v231
	v_mov_b32_e32 v36, v232
	v_mov_b32_e32 v37, v233
	s_mov_b64 s[6:7], 0xb0000
	s_nop 0
	v_lshlrev_b32_e32 v40, 16, v34
	v_and_b32_e32 v41, 0xffff0000, v34
	v_lshlrev_b32_e32 v34, 16, v35
	v_and_b32_e32 v35, 0xffff0000, v35
	v_pk_fma_f32 v[32:33], v[32:33], v[152:153], v[34:35]
	v_lshlrev_b32_e32 v34, 16, v36
	v_and_b32_e32 v35, 0xffff0000, v36
	v_pk_fma_f32 v[34:35], v[26:27], v[154:155], v[34:35]
	v_lshlrev_b32_e32 v26, 16, v37
	v_and_b32_e32 v27, 0xffff0000, v37
	v_pk_fma_f32 v[30:31], v[30:31], v[156:157], v[40:41]
	v_pk_fma_f32 v[36:37], v[28:29], v[150:151], v[26:27]
	v_cvt_pk_bf16_f32 v26, v30, v31
	v_cvt_pk_bf16_f32 v27, v32, v33
	v_cvt_pk_bf16_f32 v28, v34, v35
	v_cvt_pk_bf16_f32 v29, v36, v37
	global_store_dwordx4 v[38:39], v[26:29], off offset:2048
	s_nop 1
	v_mov_b32_e32 v26, v236
	v_mov_b32_e32 v27, v237
	v_mov_b32_e32 v28, v238
	v_mov_b32_e32 v29, v239
	s_nop 0
	v_lshlrev_b32_e32 v30, 16, v26
	v_and_b32_e32 v31, 0xffff0000, v26
	v_lshlrev_b32_e32 v26, 16, v27
	v_and_b32_e32 v27, 0xffff0000, v27
	v_pk_fma_f32 v[24:25], v[24:25], v[146:147], v[26:27]
	v_lshlrev_b32_e32 v26, 16, v28
	v_and_b32_e32 v27, 0xffff0000, v28
	v_pk_fma_f32 v[26:27], v[18:19], v[144:145], v[26:27]
	v_lshlrev_b32_e32 v18, 16, v29
	v_and_b32_e32 v19, 0xffff0000, v29
	v_pk_fma_f32 v[22:23], v[22:23], v[148:149], v[30:31]
	v_pk_fma_f32 v[28:29], v[20:21], v[142:143], v[18:19]
	v_cvt_pk_bf16_f32 v18, v22, v23
	v_cvt_pk_bf16_f32 v19, v24, v25
	v_cvt_pk_bf16_f32 v20, v26, v27
	v_cvt_pk_bf16_f32 v21, v28, v29
	global_store_dwordx4 v[38:39], v[18:21], off offset:2304
	s_nop 1
	v_lshl_add_u64 v[18:19], v[158:159], 0, s[6:7]
	v_mov_b32_e32 v20, v246
	v_mov_b32_e32 v21, v247
	v_mov_b32_e32 v22, v248
	v_mov_b32_e32 v23, v249
	s_nop 0
	v_lshlrev_b32_e32 v24, 16, v20
	v_and_b32_e32 v25, 0xffff0000, v20
	v_lshlrev_b32_e32 v20, 16, v21
	v_and_b32_e32 v21, 0xffff0000, v21
	v_pk_fma_f32 v[16:17], v[16:17], v[152:153], v[20:21]
	v_lshlrev_b32_e32 v20, 16, v22
	v_and_b32_e32 v21, 0xffff0000, v22
	v_pk_fma_f32 v[20:21], v[10:11], v[154:155], v[20:21]
	v_lshlrev_b32_e32 v10, 16, v23
	v_and_b32_e32 v11, 0xffff0000, v23
	v_pk_fma_f32 v[14:15], v[14:15], v[156:157], v[24:25]
	v_pk_fma_f32 v[22:23], v[12:13], v[150:151], v[10:11]
	v_cvt_pk_bf16_f32 v10, v14, v15
	v_cvt_pk_bf16_f32 v11, v16, v17
	v_cvt_pk_bf16_f32 v12, v20, v21
	v_cvt_pk_bf16_f32 v13, v22, v23
	global_store_dwordx4 v[18:19], v[10:13], off offset:2048
	s_nop 1
	v_mov_b32_e32 v10, v250
	v_mov_b32_e32 v11, v251
	v_mov_b32_e32 v12, v252
	v_mov_b32_e32 v13, v253
	s_nop 0
	v_lshlrev_b32_e32 v14, 16, v10
	v_and_b32_e32 v15, 0xffff0000, v10
	v_lshlrev_b32_e32 v10, 16, v11
	v_and_b32_e32 v11, 0xffff0000, v11
	v_pk_fma_f32 v[8:9], v[8:9], v[146:147], v[10:11]
	v_lshlrev_b32_e32 v10, 16, v12
	v_and_b32_e32 v11, 0xffff0000, v12
	v_pk_fma_f32 v[10:11], v[2:3], v[144:145], v[10:11]
	v_lshlrev_b32_e32 v2, 16, v13
	v_and_b32_e32 v3, 0xffff0000, v13
	v_pk_fma_f32 v[6:7], v[6:7], v[148:149], v[14:15]
	v_pk_fma_f32 v[12:13], v[4:5], v[142:143], v[2:3]
	v_cvt_pk_bf16_f32 v2, v6, v7
	v_cvt_pk_bf16_f32 v3, v8, v9
	v_cvt_pk_bf16_f32 v4, v10, v11
	v_cvt_pk_bf16_f32 v5, v12, v13
	global_store_dwordx4 v[18:19], v[2:5], off offset:2304
	s_cbranch_vccz .LBB0_1399
	s_waitcnt vmcnt(0)
	s_cmpk_gt_u32 s22, 0xff
	s_cbranch_scc1 .LBB0_1412
	s_barrier
